# attention: waves 4-7 barrier/commit rotated to after QK (K 2 slots, V 3 slots) AND all s_setprio toggles removed so the partner wave's VALU is not starved; max3 row-max
# baseline (speedup 1.0000x reference)
; #define LAS __attribute__((address_space(3)))
; #define AT_LDK(buf, grp) do { _Pragma("unroll") for (int q_ = 0; q_ < 2; ++q_) { kf[buf][2 * q_] = *(const LAS bf16x8*)(ka + ((grp) * 2 + q_) * 32); kf[buf][2 * q_ + 1] = *(const LAS bf16x8*)(ka + 32 * AT_KROW + ((grp) * 2 + q_) * 32); } } while (0)
; __device__ __forceinline__ void attn_phase(LAS unsigned char* lds, const bf16* Q, const bf16* KV, const bf16* KPE, const float* rope, bf16* mix, int bid, int G, int tid) {
;     ...
;         for (int kt = 0; kt < ntiles; ++kt) {
;             if (kt + 1 < ntiles) AT_ISSUE(kt + 1);
;             const int key0 = kt * 64;
;             const LAS unsigned char* kb_ = lds + (kt & 1) * AT_BUF; const LAS unsigned char* vb_ = kb_ + AT_KB;
;             if (key0 <= qlo + 31) {
;                 f32x16 S0, S1;
; #pragma unroll
;                 for (int e = 0; e < 16; ++e) { S0[e] = 0.f; S1[e] = 0.f; }
;                 const LAS unsigned char* ka = kb_ + l32 * AT_KROW + hh * 16;
;                 bf16x8 kf[2][4];
;     ...
;                 AT_LDK(0, 0); __builtin_amdgcn_sched_barrier(0);
; #pragma unroll
;                 for (int grp = 0; grp < 6; ++grp) {
;                     if (grp < 5) { AT_LDK((grp + 1) & 1, grp + 1); }
;                     __builtin_amdgcn_sched_barrier(0);
;                     __builtin_amdgcn_s_setprio(1);
; #pragma unroll
;                     for (int q_ = 0; q_ < 2; ++q_) {
;                         S0 = __builtin_amdgcn_mfma_f32_32x32x16_bf16(kf[grp & 1][2 * q_], qf[grp * 2 + q_], S0, 0, 0, 0);
;                         S1 = __builtin_amdgcn_mfma_f32_32x32x16_bf16(kf[grp & 1][2 * q_ + 1], qf[grp * 2 + q_], S1, 0, 0, 0); }
;                     __builtin_amdgcn_s_setprio(0);
;                     __builtin_amdgcn_sched_barrier(0); }
;     ...
;                 const LAS unsigned char* va = vb_ + (4 * hh + ((lane & 15) >> 2)) * AT_VROW + (16 * ((lane >> 4) & 1) + 4 * (lane & 3)) * 2;
;                 s16x4 vf[2][4];
;     ...
;                 AT_LDV(0, 0); __builtin_amdgcn_sched_barrier(0);
;                 if (key0 + 63 > qlo) { const int qq = qlo + l32;
; #pragma unroll
;                     for (int e = 0; e < 16; ++e) { const int key = key0 + 8 * (e >> 2) + 4 * hh + (e & 3);
;                         if (key > qq) S0[e] = -1e30f; if (key + 32 > qq) S1[e] = -1e30f; } }
;     ...
;             if (kt + 1 < ntiles) AT_COMMIT(lds + ((kt + 1) & 1) * AT_BUF);
.LBB0_253:
	s_sub_i32 s5, s0, 63
	s_cmp_gt_i32 s5, s11
	s_cbranch_scc1 .LBB0_259
	s_bitcmp1_b32 s4, 0
	s_cselect_b32 s4, 0x6400, 0
	v_add3_u32 v236, s4, v203, v96
	ds_read_b128 v[64:67], v236
	ds_read_b128 v[166:169], v236 offset:32
	ds_read_b128 v[68:71], v236 offset:12800
	ds_read_b128 v[170:173], v236 offset:12832
	ds_read_b128 v[208:211], v236 offset:64
	ds_read_b128 v[212:215], v236 offset:96
	ds_read_b128 v[228:231], v236 offset:12864
	ds_read_b128 v[232:235], v236 offset:12896
	s_waitcnt lgkmcnt(0)
	v_mfma_f32_32x32x16_bf16 v[80:95], v[64:67], v[98:101], 0
	v_mfma_f32_32x32x16_bf16 v[64:79], v[68:71], v[98:101], 0
	v_mfma_f32_32x32x16_bf16 v[80:95], v[166:169], v[102:105], v[80:95]
	v_mfma_f32_32x32x16_bf16 v[64:79], v[170:173], v[102:105], v[64:79]
	ds_read_b128 v[166:169], v236 offset:128
	ds_read_b128 v[170:173], v236 offset:160
	ds_read_b128 v[242:245], v236 offset:12928
	ds_read_b128 v[246:249], v236 offset:12960
	v_mfma_f32_32x32x16_bf16 v[80:95], v[208:211], v[106:109], v[80:95]
	v_mfma_f32_32x32x16_bf16 v[64:79], v[228:231], v[106:109], v[64:79]
	v_mfma_f32_32x32x16_bf16 v[80:95], v[212:215], v[110:113], v[80:95]
	v_mfma_f32_32x32x16_bf16 v[64:79], v[232:235], v[110:113], v[64:79]
	ds_read_b128 v[208:211], v236 offset:192
	ds_read_b128 v[212:215], v236 offset:224
	ds_read_b128 v[228:231], v236 offset:12992
	ds_read_b128 v[232:235], v236 offset:13024
	s_waitcnt lgkmcnt(0)
	v_mfma_f32_32x32x16_bf16 v[80:95], v[166:169], v[114:117], v[80:95]
	v_mfma_f32_32x32x16_bf16 v[64:79], v[242:245], v[114:117], v[64:79]
	v_mfma_f32_32x32x16_bf16 v[80:95], v[170:173], v[118:121], v[80:95]
	v_mfma_f32_32x32x16_bf16 v[64:79], v[246:249], v[118:121], v[64:79]
	ds_read_b128 v[166:169], v236 offset:256
	ds_read_b128 v[170:173], v236 offset:288
	ds_read_b128 v[242:245], v236 offset:13056
	ds_read_b128 v[246:249], v236 offset:13088
	v_mfma_f32_32x32x16_bf16 v[80:95], v[208:211], v[122:125], v[80:95]
	v_mfma_f32_32x32x16_bf16 v[64:79], v[228:231], v[122:125], v[64:79]
	v_mfma_f32_32x32x16_bf16 v[80:95], v[212:215], v[126:129], v[80:95]
	v_mfma_f32_32x32x16_bf16 v[64:79], v[232:235], v[126:129], v[64:79]
	ds_read_b128 v[208:211], v236 offset:320
	ds_read_b128 v[212:215], v236 offset:352
	ds_read_b128 v[228:231], v236 offset:13120
	ds_read_b128 v[232:235], v236 offset:13152
	s_waitcnt lgkmcnt(0)
	v_mfma_f32_32x32x16_bf16 v[80:95], v[166:169], v[130:133], v[80:95]
	v_mfma_f32_32x32x16_bf16 v[64:79], v[242:245], v[130:133], v[64:79]
	v_mfma_f32_32x32x16_bf16 v[80:95], v[170:173], v[158:161], v[80:95]
	v_mfma_f32_32x32x16_bf16 v[64:79], v[246:249], v[158:161], v[64:79]
	v_mfma_f32_32x32x16_bf16 v[80:95], v[208:211], v[134:137], v[80:95]
	v_add_u32_e32 v166, s14, v204
	v_add_u32_e32 v208, v166, v205
	ds_read_b64_tr_b16 v[170:171], v208 offset:25600
	ds_read_b64_tr_b16 v[172:173], v208 offset:28160
	ds_read_b64_tr_b16 v[168:169], v208 offset:28224
	ds_read_b64_tr_b16 v[166:167], v208 offset:25664
	v_mfma_f32_32x32x16_bf16 v[64:79], v[228:231], v[134:137], v[64:79]
	v_mfma_f32_32x32x16_bf16 v[80:95], v[212:215], v[162:165], v[80:95]
	v_mfma_f32_32x32x16_bf16 v[64:79], v[232:235], v[162:165], v[64:79]
	s_cmp_eq_u32 s17, 0
	s_cbranch_scc1 .Latt_xa
	s_andn2_b64 vcc, exec, s[34:35]
	s_cbranch_vccnz .Latt_xnc_a
	s_bitcmp1_b32 s1, 0
	s_cselect_b32 s4, 0x6400, 0
	s_add_i32 s15, s14, 0x5000
	s_cmp_gt_u32 s15, 0x10400
	s_cselect_b32 s15, 0x6400, s15
	v_add3_u32 v250, s4, v190, v187
	s_waitcnt vmcnt(0) lgkmcnt(0)
	ds_write_b128 v250, v[138:141]
	v_add3_u32 v250, s4, v191, v187
	ds_write_b128 v250, v[142:145]
	v_add3_u32 v250, s4, v192, v188
	ds_write_b128 v250, v[150:153] offset:256
	v_add3_u32 v250, s15, v193, v187
	ds_write_b128 v250, v[146:149] offset:25600
	v_add3_u32 v250, s15, v202, v187
	ds_write_b128 v250, v[154:157] offset:25600

; __device__ __forceinline__ u32x4 pack8(const float (&f)[8]) { u32x4 w; w.x = pk_bf16(f[0], f[1]); w.y = pk_bf16(f[2], f[3]); w.z = pk_bf16(f[4], f[5]); w.w = pk_bf16(f[6], f[7]); return w; }
; #define AT_LDV(buf, hs) do { const LAS unsigned char* vp_ = va + ((((hs) >> 1) >> 1) * 32 + 16 * (((hs) >> 1) & 1)) * AT_VROW + ((hs) & 1) * 128; _Pragma("unroll") for (int d_ = 0; d_ < 2; ++d_) { vf[buf][2 * d_] = vtr(vp_ + d_ * 64); vf[buf][2 * d_ + 1] = vtr(vp_ + 8 * AT_VROW + d_ * 64); } } while (0)
; __device__ __forceinline__ void attn_phase(LAS unsigned char* lds, const bf16* Q, const bf16* KV, const bf16* KPE, const float* rope, bf16* mix, int bid, int G, int tid) {
;     ...
;                 const float alpha = __builtin_amdgcn_exp2f(mrun - mnew); mrun = mnew;
;                 float rs = 0.f;
; #pragma unroll
;                 for (int e = 0; e < 16; ++e) { S0[e] = __builtin_amdgcn_exp2f(S0[e] - mnew); S1[e] = __builtin_amdgcn_exp2f(S1[e] - mnew); rs += S0[e] + S1[e]; }
;                 lrun = lrun * alpha + rs;
;                 if (__builtin_amdgcn_ballot_w64(alpha != 1.0f) != 0ull) {
; #pragma unroll
;                     for (int i = 0; i < 4; ++i)
; #pragma unroll
;                         for (int e = 0; e < 16; ++e) O[i][e] *= alpha; }
; #pragma unroll
;                 for (int hs = 0; hs < 8; ++hs) { const int st = hs >> 1;
;                     if (hs < 7) { AT_LDV((hs + 1) & 1, hs + 1); }
;                     __builtin_amdgcn_sched_barrier(0);
;                     float pf[8];
; #pragma unroll
;                     for (int e = 0; e < 8; ++e) pf[e] = (st >> 1) ? S1[8 * (st & 1) + e] : S0[8 * (st & 1) + e];
;                     const bf16x8 pb = __builtin_bit_cast(bf16x8, pack8(pf));
; #pragma unroll
;                     for (int d_ = 0; d_ < 2; ++d_) { const int dvt = (hs & 1) * 2 + d_; const s16x4 lo = vf[hs & 1][2 * d_], hi = vf[hs & 1][2 * d_ + 1];
;                         const bf16x8 A = (bf16x8){lo[0], lo[1], lo[2], lo[3], hi[0], hi[1], hi[2], hi[3]};
;                         __builtin_amdgcn_s_setprio(1); O[dvt] = __builtin_amdgcn_mfma_f32_32x32x16_bf16(A, pb, O[dvt], 0, 0, 0); __builtin_amdgcn_s_setprio(0); }
;                     __builtin_amdgcn_sched_barrier(0); }
.LBB0_258:
	v_sub_f32_e32 v80, v80, v209
	v_sub_f32_e32 v64, v64, v209
	v_exp_f32_e32 v80, v80
	v_exp_f32_e32 v210, v64
	v_sub_f32_e32 v81, v81, v209
	v_sub_f32_e32 v65, v65, v209
	v_exp_f32_e32 v81, v81
	v_exp_f32_e32 v211, v65
	v_add_f32_e32 v64, v80, v210
	v_add_f32_e32 v64, 0, v64
	v_add_f32_e32 v65, v81, v211
	v_add_f32_e32 v64, v65, v64
	v_sub_f32_e32 v65, v82, v209
	v_exp_f32_e32 v82, v65
	v_sub_f32_e32 v65, v66, v209
	v_exp_f32_e32 v212, v65
	s_nop 0
	v_add_f32_e32 v65, v82, v212
	v_add_f32_e32 v64, v65, v64
	v_sub_f32_e32 v65, v83, v209
	v_exp_f32_e32 v83, v65
	v_sub_f32_e32 v65, v67, v209
	v_exp_f32_e32 v213, v65
	s_nop 0
	v_add_f32_e32 v65, v83, v213
	v_add_f32_e32 v64, v65, v64
	v_sub_f32_e32 v65, v84, v209
	v_exp_f32_e32 v84, v65
	v_sub_f32_e32 v65, v68, v209
	v_exp_f32_e32 v214, v65
	s_nop 0
	v_add_f32_e32 v65, v84, v214
	v_add_f32_e32 v64, v65, v64
	v_sub_f32_e32 v65, v85, v209
	v_exp_f32_e32 v85, v65
	v_sub_f32_e32 v65, v69, v209
	v_exp_f32_e32 v215, v65
	s_nop 0
	v_add_f32_e32 v65, v85, v215
	v_add_f32_e32 v64, v65, v64
	v_sub_f32_e32 v65, v86, v209
	v_exp_f32_e32 v86, v65
	v_sub_f32_e32 v65, v70, v209
	v_exp_f32_e32 v228, v65
	s_nop 0
	v_add_f32_e32 v65, v86, v228
	v_add_f32_e32 v64, v65, v64
	v_sub_f32_e32 v65, v87, v209
	v_exp_f32_e32 v87, v65
	v_sub_f32_e32 v65, v71, v209
	v_exp_f32_e32 v229, v65
	s_nop 0
	v_add_f32_e32 v65, v87, v229
	v_add_f32_e32 v64, v65, v64
	v_sub_f32_e32 v65, v88, v209
	v_exp_f32_e32 v88, v65
	v_sub_f32_e32 v65, v72, v209
	v_exp_f32_e32 v230, v65
	s_nop 0
	v_add_f32_e32 v65, v88, v230
	v_add_f32_e32 v64, v65, v64
	v_sub_f32_e32 v65, v89, v209
	v_exp_f32_e32 v89, v65
	v_sub_f32_e32 v65, v73, v209
	v_exp_f32_e32 v231, v65
	s_nop 0
	v_add_f32_e32 v65, v89, v231
	v_add_f32_e32 v64, v65, v64
	v_sub_f32_e32 v65, v90, v209
	v_exp_f32_e32 v90, v65
	v_sub_f32_e32 v65, v74, v209
	v_exp_f32_e32 v232, v65
	s_nop 0
	v_add_f32_e32 v65, v90, v232
	v_add_f32_e32 v64, v65, v64
	v_sub_f32_e32 v65, v91, v209
	v_exp_f32_e32 v91, v65
	v_sub_f32_e32 v65, v75, v209
	v_exp_f32_e32 v233, v65
	s_nop 0
	v_add_f32_e32 v65, v91, v233
	v_add_f32_e32 v64, v65, v64
	v_sub_f32_e32 v65, v92, v209
	v_exp_f32_e32 v92, v65
	v_sub_f32_e32 v65, v76, v209
	v_exp_f32_e32 v234, v65
	s_nop 0
	v_add_f32_e32 v65, v92, v234
	v_add_f32_e32 v64, v65, v64
	v_sub_f32_e32 v65, v93, v209
	v_exp_f32_e32 v93, v65
	v_sub_f32_e32 v65, v77, v209
	v_exp_f32_e32 v235, v65
	s_nop 0
	v_add_f32_e32 v65, v93, v235
	v_add_f32_e32 v64, v65, v64
	v_sub_f32_e32 v65, v94, v209
	v_exp_f32_e32 v94, v65
	v_sub_f32_e32 v65, v78, v209
	v_exp_f32_e32 v236, v65
	s_nop 0
	v_add_f32_e32 v65, v94, v236
	v_add_f32_e32 v64, v65, v64
	v_sub_f32_e32 v65, v95, v209
	v_exp_f32_e32 v95, v65
	v_sub_f32_e32 v65, v79, v209
	v_exp_f32_e32 v237, v65
	s_nop 0
	v_add_f32_e32 v65, v95, v237
	v_add_f32_e32 v242, v65, v64
	ds_read_b64_tr_b16 v[64:65], v208 offset:25728
	ds_read_b64_tr_b16 v[66:67], v208 offset:28288
	ds_read_b64_tr_b16 v[68:69], v208 offset:25792
	ds_read_b64_tr_b16 v[70:71], v208 offset:28352
	v_fmac_f32_e32 v242, v207, v184
	v_cvt_pk_bf16_f32 v72, v80, v81
	v_cvt_pk_bf16_f32 v73, v82, v83
	v_cvt_pk_bf16_f32 v74, v84, v85
	v_cvt_pk_bf16_f32 v75, v86, v87
	s_nop 1
	v_mfma_f32_32x32x16_bf16 v[48:63], v[170:173], v[72:75], v[48:63]
	v_mfma_f32_32x32x16_bf16 v[32:47], v[166:169], v[72:75], v[32:47]
	ds_read_b64_tr_b16 v[76:77], v208 offset:30720
	ds_read_b64_tr_b16 v[78:79], v208 offset:33280
	ds_read_b64_tr_b16 v[80:81], v208 offset:30784
	ds_read_b64_tr_b16 v[82:83], v208 offset:33344
	s_waitcnt lgkmcnt(0)
	v_mfma_f32_32x32x16_bf16 v[16:31], v[64:67], v[72:75], v[16:31]
	v_mfma_f32_32x32x16_bf16 v[0:15], v[68:71], v[72:75], v[0:15]
	ds_read_b64_tr_b16 v[64:65], v208 offset:30848
	ds_read_b64_tr_b16 v[66:67], v208 offset:33408
	ds_read_b64_tr_b16 v[68:69], v208 offset:30912
	ds_read_b64_tr_b16 v[70:71], v208 offset:33472
	v_cvt_pk_bf16_f32 v72, v88, v89
	v_cvt_pk_bf16_f32 v73, v90, v91
	v_cvt_pk_bf16_f32 v74, v92, v93
	v_cvt_pk_bf16_f32 v75, v94, v95
	s_nop 1
	v_mfma_f32_32x32x16_bf16 v[48:63], v[76:79], v[72:75], v[48:63]
	v_mfma_f32_32x32x16_bf16 v[32:47], v[80:83], v[72:75], v[32:47]
	ds_read_b64_tr_b16 v[76:77], v208 offset:35840
	ds_read_b64_tr_b16 v[78:79], v208 offset:38400
	ds_read_b64_tr_b16 v[82:83], v208 offset:38464
	ds_read_b64_tr_b16 v[80:81], v208 offset:35904
	s_waitcnt lgkmcnt(0)
	v_mfma_f32_32x32x16_bf16 v[16:31], v[64:67], v[72:75], v[16:31]
	v_mfma_f32_32x32x16_bf16 v[0:15], v[68:71], v[72:75], v[0:15]
	ds_read_b64_tr_b16 v[64:65], v208 offset:35968
	ds_read_b64_tr_b16 v[66:67], v208 offset:38528
	ds_read_b64_tr_b16 v[70:71], v208 offset:38592
	ds_read_b64_tr_b16 v[68:69], v208 offset:36032
	v_cvt_pk_bf16_f32 v72, v210, v211
	v_cvt_pk_bf16_f32 v73, v212, v213
	v_cvt_pk_bf16_f32 v74, v214, v215
	v_cvt_pk_bf16_f32 v75, v228, v229
	s_nop 1
	v_mfma_f32_32x32x16_bf16 v[48:63], v[76:79], v[72:75], v[48:63]
	v_mfma_f32_32x32x16_bf16 v[32:47], v[80:83], v[72:75], v[32:47]
	ds_read_b64_tr_b16 v[76:77], v208 offset:40960
	ds_read_b64_tr_b16 v[78:79], v208 offset:43520
	ds_read_b64_tr_b16 v[82:83], v208 offset:43584
	ds_read_b64_tr_b16 v[80:81], v208 offset:41024
	s_waitcnt lgkmcnt(0)
	v_mfma_f32_32x32x16_bf16 v[16:31], v[64:67], v[72:75], v[16:31]
	v_mfma_f32_32x32x16_bf16 v[0:15], v[68:71], v[72:75], v[0:15]
	ds_read_b64_tr_b16 v[64:65], v208 offset:41088
	ds_read_b64_tr_b16 v[66:67], v208 offset:43648
	ds_read_b64_tr_b16 v[70:71], v208 offset:43712
	ds_read_b64_tr_b16 v[68:69], v208 offset:41152
	v_cvt_pk_bf16_f32 v72, v230, v231
	v_cvt_pk_bf16_f32 v73, v232, v233
	v_cvt_pk_bf16_f32 v74, v234, v235
	v_cvt_pk_bf16_f32 v75, v236, v237
	s_nop 1
	v_mfma_f32_32x32x16_bf16 v[48:63], v[76:79], v[72:75], v[48:63]
	v_mfma_f32_32x32x16_bf16 v[32:47], v[80:83], v[72:75], v[32:47]
	s_waitcnt lgkmcnt(0)
	v_mfma_f32_32x32x16_bf16 v[16:31], v[64:67], v[72:75], v[16:31]
	v_mfma_f32_32x32x16_bf16 v[0:15], v[68:71], v[72:75], v[0:15]
	v_mov_b32_e32 v207, v242
	s_branch .LBB0_260
